# grid barrier: waiting workgroups poll the top-level counter directly instead of their group's generation word (one hop less)
# baseline (speedup 1.0000x reference)
.LBB0_122:
	s_or_b64 exec, exec, s[4:5]
	v_cvt_f32_u32_e32 v4, v2
	s_waitcnt vmcnt(0)
	v_readfirstlane_b32 s2, v3
	v_sub_u32_e32 v3, 0, v2
	v_rcp_iflag_f32_e32 v4, v4
	v_add_u32_e32 v5, s2, v1
	v_mul_f32_e32 v4, 0x4f7ffffe, v4
	v_cvt_u32_f32_e32 v4, v4
	v_mul_lo_u32 v1, v3, v4
	v_mul_hi_u32 v1, v4, v1
	v_add_u32_e32 v1, v4, v1
	v_mul_hi_u32 v1, v5, v1
	v_mul_lo_u32 v3, v1, v2
	v_sub_u32_e32 v3, v5, v3
	v_add_u32_e32 v4, 1, v1
	v_sub_u32_e32 v6, v3, v2
	v_cmp_ge_u32_e32 vcc, v3, v2
	s_nop 1
	v_cndmask_b32_e32 v1, v1, v4, vcc
	v_cndmask_b32_e32 v3, v3, v6, vcc
	v_add_u32_e32 v4, 1, v1
	v_cmp_ge_u32_e32 vcc, v3, v2
	v_add_u32_e32 v3, 1, v5
	s_nop 0
	v_cndmask_b32_e32 v1, v1, v4, vcc
	v_mul_lo_u32 v4, v2, v1
	v_add_u32_e32 v2, v4, v2
	v_cmp_ne_u32_e32 vcc, v3, v2
	s_and_saveexec_b64 s[2:3], vcc
	s_xor_b64 s[2:3], exec, s[2:3]
	s_cbranch_execz .LBB0_136
	v_readfirstlane_b32 s98, v1
	v_readfirstlane_b32 s99, v0
	s_add_u32 s98, s98, 1
	s_mul_i32 s98, s98, s99
	v_readlane_b32 s100, v254, 52
	v_readlane_b32 s101, v254, 53
	v_mov_b32_e32 v2, 0
	s_mov_b32 s99, 0
	s_nop 3
.Lmy_w_spin_1:
	global_load_dword v0, v2, s[100:101] sc1
	s_waitcnt vmcnt(0)
	v_readfirstlane_b32 s4, v0
	s_cmp_lt_u32 s4, s98
	s_cbranch_scc0 .Lmy_w_done_1
	s_sleep 1
	s_add_u32 s99, s99, 1
	s_cmp_lt_u32 s99, 0x100000
	s_cbranch_scc1 .Lmy_w_spin_1
.Lmy_w_done_1:
.LBB0_136:
	s_andn2_saveexec_b64 s[2:3], s[2:3]
	s_cbranch_execz .LBB0_156
	s_mov_b64 s[2:3], exec
	buffer_wbl2 sc1
	s_waitcnt lgkmcnt(0)
	s_waitcnt vmcnt(0)
	v_readfirstlane_b32 s98, v1
	v_readfirstlane_b32 s99, v0
	s_add_u32 s98, s98, 1
	s_mul_i32 s98, s98, s99
	v_readlane_b32 s100, v254, 52
	v_readlane_b32 s101, v254, 53
	v_mov_b32_e32 v2, 0
	v_mov_b32_e32 v3, 1
	s_nop 3
	global_atomic_add v2, v3, s[100:101]
	s_mov_b32 s99, 0

.LBB0_206:
	s_or_b64 exec, exec, s[6:7]
	v_cvt_f32_u32_e32 v4, v2
	s_waitcnt vmcnt(0)
	v_readfirstlane_b32 s4, v3
	v_sub_u32_e32 v3, 0, v2
	v_rcp_iflag_f32_e32 v4, v4
	v_add_u32_e32 v5, s4, v1
	v_mul_f32_e32 v4, 0x4f7ffffe, v4
	v_cvt_u32_f32_e32 v4, v4
	v_mul_lo_u32 v1, v3, v4
	v_mul_hi_u32 v1, v4, v1
	v_add_u32_e32 v1, v4, v1
	v_mul_hi_u32 v1, v5, v1
	v_mul_lo_u32 v3, v1, v2
	v_sub_u32_e32 v3, v5, v3
	v_add_u32_e32 v4, 1, v1
	v_cmp_ge_u32_e32 vcc, v3, v2
	s_nop 1
	v_cndmask_b32_e32 v1, v1, v4, vcc
	v_sub_u32_e32 v4, v3, v2
	v_cndmask_b32_e32 v3, v3, v4, vcc
	v_add_u32_e32 v4, 1, v1
	v_cmp_ge_u32_e32 vcc, v3, v2
	v_add_u32_e32 v3, 1, v5
	s_nop 0
	v_cndmask_b32_e32 v1, v1, v4, vcc
	v_mul_lo_u32 v4, v2, v1
	v_add_u32_e32 v2, v4, v2
	v_cmp_ne_u32_e32 vcc, v3, v2
	s_and_saveexec_b64 s[4:5], vcc
	s_xor_b64 s[4:5], exec, s[4:5]
	s_cbranch_execz .LBB0_220
	v_readfirstlane_b32 s98, v1
	v_readfirstlane_b32 s99, v0
	s_add_u32 s98, s98, 1
	s_mul_i32 s98, s98, s99
	v_readlane_b32 s100, v254, 52
	v_readlane_b32 s101, v254, 53
	v_mov_b32_e32 v2, 0
	s_mov_b32 s99, 0
	s_nop 3
.Lmy_w_spin_2:
	global_load_dword v0, v2, s[100:101] sc1
	s_waitcnt vmcnt(0)
	v_readfirstlane_b32 s6, v0
	s_cmp_lt_u32 s6, s98
	s_cbranch_scc0 .Lmy_w_done_2
	s_sleep 1
	s_add_u32 s99, s99, 1
	s_cmp_lt_u32 s99, 0x100000
	s_cbranch_scc1 .Lmy_w_spin_2
.Lmy_w_done_2:
.LBB0_220:
	s_andn2_saveexec_b64 s[4:5], s[4:5]
	s_cbranch_execz .LBB0_240
	s_mov_b64 s[4:5], exec
	buffer_wbl2 sc1
	s_waitcnt lgkmcnt(0)
	s_waitcnt vmcnt(0)
	v_readfirstlane_b32 s98, v1
	v_readfirstlane_b32 s99, v0
	s_add_u32 s98, s98, 1
	s_mul_i32 s98, s98, s99
	v_readlane_b32 s100, v254, 52
	v_readlane_b32 s101, v254, 53
	v_mov_b32_e32 v2, 0
	v_mov_b32_e32 v3, 1
	s_nop 3
	global_atomic_add v2, v3, s[100:101]
	s_mov_b32 s99, 0

.LBB0_381:
	s_or_b64 exec, exec, s[4:5]
	v_cvt_f32_u32_e32 v4, v2
	s_waitcnt vmcnt(0)
	v_readfirstlane_b32 s2, v3
	v_sub_u32_e32 v3, 0, v2
	v_rcp_iflag_f32_e32 v4, v4
	v_add_u32_e32 v5, s2, v1
	v_mul_f32_e32 v4, 0x4f7ffffe, v4
	v_cvt_u32_f32_e32 v4, v4
	v_mul_lo_u32 v1, v3, v4
	v_mul_hi_u32 v1, v4, v1
	v_add_u32_e32 v1, v4, v1
	v_mul_hi_u32 v1, v5, v1
	v_mul_lo_u32 v3, v1, v2
	v_sub_u32_e32 v3, v5, v3
	v_add_u32_e32 v4, 1, v1
	v_cmp_ge_u32_e32 vcc, v3, v2
	s_nop 1
	v_cndmask_b32_e32 v1, v1, v4, vcc
	v_sub_u32_e32 v4, v3, v2
	v_cndmask_b32_e32 v3, v3, v4, vcc
	v_add_u32_e32 v4, 1, v1
	v_cmp_ge_u32_e32 vcc, v3, v2
	v_add_u32_e32 v3, 1, v5
	s_nop 0
	v_cndmask_b32_e32 v1, v1, v4, vcc
	v_mul_lo_u32 v4, v2, v1
	v_add_u32_e32 v2, v4, v2
	v_cmp_ne_u32_e32 vcc, v3, v2
	s_and_saveexec_b64 s[2:3], vcc
	s_xor_b64 s[2:3], exec, s[2:3]
	s_cbranch_execz .LBB0_395
	v_readfirstlane_b32 s98, v1
	v_readfirstlane_b32 s99, v0
	s_add_u32 s98, s98, 1
	s_mul_i32 s98, s98, s99
	v_readlane_b32 s100, v254, 52
	v_readlane_b32 s101, v254, 53
	v_mov_b32_e32 v2, 0
	s_mov_b32 s99, 0
	s_nop 3
